# latent attention loop: K/V tiles staged by LDS-DMA (K at half-iteration top, V after barrier 1) instead of global->VGPR->ds_write
# speedup vs baseline: 1.0077x; 1.0077x over previous
.LBB0_853:
	s_and_b64 vcc, exec, s[0:1]
	s_cbranch_vccz .LBB0_820
	s_ashr_i32 s14, s49, 5
	s_ashr_i32 s15, s14, 31
	s_lshl_b32 s0, s49, 8
	s_lshl_b64 s[42:43], s[14:15], 11
	s_and_b32 s0, s0, 0x700
	s_or_b32 s42, s42, s0
	s_mul_i32 s0, s43, 0x600
	s_mul_hi_u32 s1, s42, 0x600
	s_bfe_u32 s4, s49, 0x20003
	s_add_i32 s1, s1, s0
	s_mul_i32 s0, s42, 0x600
	s_add_u32 s0, s84, s0
	s_addc_u32 s1, s85, s1
	s_mul_i32 s2, s4, 0x180
	s_add_u32 s16, s0, s2
	s_addc_u32 s17, s1, 0
	v_readlane_b32 s0, v251, 48
	v_readlane_b32 s1, v251, 49
	s_add_u32 s2, s0, s2
	s_addc_u32 s8, s1, 0
	s_lshl_b32 s7, s4, 7
	s_lshl_b32 s0, s4, 8
	v_readlane_b32 s10, v253, 7
	v_mov_b32_e32 v170, v0
	v_readlane_b32 s11, v253, 8
	s_add_u32 s9, s10, s0
	s_addc_u32 s10, s11, 0
	v_ashrrev_i32_e32 v161, 6, v170
	v_and_b32_e32 v172, 31, v170
	v_and_b32_e32 v2, 0x3fffffc0, v170
	s_add_i32 s1, 0, 0x14000
	v_lshlrev_b32_e32 v160, 5, v161
	v_bfe_u32 v173, v170, 5, 1
	v_lshl_add_u32 v64, v2, 2, s1
	v_or_b32_e32 v4, v160, v172
	s_waitcnt lgkmcnt(0)
	v_mov_b64_e32 v[2:3], s[16:17]
	s_movk_i32 s11, 0x600
	v_mad_i64_i32 v[2:3], s[16:17], v4, s11, v[2:3]
	v_lshlrev_b32_e32 v62, 4, v173
	v_mov_b32_e32 v63, v99
	v_lshl_add_u64 v[6:7], v[2:3], 0, v[62:63]
	v_lshlrev_b32_e32 v2, 12, v161
	s_add_i32 s1, 0, 0x14800
	v_lshlrev_b32_e32 v3, 7, v172
	global_load_dwordx4 v[128:131], v[6:7], off
	global_load_dwordx4 v[124:127], v[6:7], off offset:32
	global_load_dwordx4 v[120:123], v[6:7], off offset:64
	global_load_dwordx4 v[116:119], v[6:7], off offset:96
	global_load_dwordx4 v[112:115], v[6:7], off offset:128
	global_load_dwordx4 v[108:111], v[6:7], off offset:160
	global_load_dwordx4 v[104:107], v[6:7], off offset:192
	global_load_dwordx4 v[100:103], v[6:7], off offset:224
	v_add3_u32 v51, s1, v2, v3
	global_load_dwordx4 v[2:5], v[6:7], off offset:256
	global_load_dwordx4 v[132:135], v[6:7], off offset:288
	global_load_dwordx4 v[136:139], v[6:7], off offset:320
	global_load_dwordx4 v[140:143], v[6:7], off offset:352
	v_bitop3_b32 v8, v173, v170, 7 bitop3:0x78
	v_lshl_add_u32 v8, v8, 4, v51
	v_lshlrev_b32_e32 v14, 4, v170
	v_and_b32_e32 v50, 0x70, v14
	s_movk_i32 s1, 0x60
	s_movk_i32 s18, 0x180
	s_lshl_b32 s12, s14, 8
	s_add_i32 s0, s12, 0x4000
	s_lshl_b32 s13, s14, 11
	s_cmp_lg_u32 0, -1
	s_mul_i32 s15, s14, 0x60000
	s_cselect_b32 s14, 0, 0
	v_and_b32_e32 v171, 63, v170
	v_mul_u32_u24_e32 v55, 0x180, v172
	v_or_b32_e32 v52, 32, v62
	v_bitop3_b32 v56, v52, v55, v50 bitop3:0xde
	v_add_u32_e32 v184, 0, v56
	v_or_b32_e32 v53, 64, v62
	v_or_b32_e32 v54, 0x60, v62
	s_mov_b32 s68, s69
	s_mov_b32 s70, s69
	s_mov_b32 s71, s69
	s_mov_b32 s72, s69
	s_mov_b32 s73, s69
	s_mov_b32 s74, s69
	s_mov_b32 s75, s69
	s_mov_b32 s76, s69
	s_mov_b32 s77, s69
	s_mov_b32 s78, s69
	s_mov_b32 s79, s69
	s_mov_b32 s80, s69
	s_mov_b32 s81, s69
	s_mov_b32 s82, s69
	s_mov_b32 s83, s69
	v_lshl_add_u32 v197, v172, 2, v64
	v_add_u32_e32 v193, v64, v62
	v_mov_b32_e32 v212, 0x358637bd
	v_mov_b32_e32 v200, 0xff
	v_mov_b32_e32 v202, 0x1b00
	v_mov_b32_e32 v201, 0x600
	v_mov_b32_e32 v203, 0x260
	v_mov_b32_e32 v169, v99
	v_mov_b32_e32 v163, v99
	v_mov_b32_e32 v165, v99
	v_mov_b32_e32 v167, v99
	v_cmp_gt_u32_e64 s[38:39], 32, v171
	v_mov_b32_e32 v198, 0
	s_waitcnt vmcnt(0)
	ds_write_b128 v8, v[2:5]
	v_bitop3_b32 v8, v62, v50, 32 bitop3:0x36
	v_add_u32_e32 v176, v51, v8
	v_bitop3_b32 v8, v62, v50, 64 bitop3:0x36
	v_add_u32_e32 v177, v51, v8
	ds_write_b128 v176, v[132:135]
	ds_write_b128 v177, v[136:139]
	v_bitop3_b32 v6, v62, v50, s1 bitop3:0x36
	v_add_u32_e32 v175, v51, v6
	s_mov_b32 s1, 0x2aaaaaab
	ds_write_b128 v175, v[140:143]
	v_ashrrev_i32_e32 v2, 4, v170
	v_and_b32_e32 v5, 0xfffff0, v2
	v_lshlrev_b32_e32 v6, 1, v2
	v_and_or_b32 v5, v6, 8, v5
	v_lshrrev_b32_e32 v6, 1, v2
	v_and_b32_e32 v7, 3, v2
	v_and_or_b32 v6, v6, 4, v7
	v_add_u32_e32 v7, 32, v2
	v_and_b32_e32 v8, 0xfffff0, v7
	v_lshlrev_b32_e32 v7, 1, v7
	v_lshlrev_b32_e32 v3, 3, v170
	v_and_or_b32 v7, v7, 8, v8
	v_and_b32_e32 v4, 0x78, v3
	v_lshrrev_b32_e32 v5, 1, v5
	v_bfe_u32 v3, v3, 5, 2
	v_lshrrev_b32_e32 v7, 1, v7
	v_or_b32_e32 v5, v5, v3
	v_or_b32_e32 v3, v7, v3
	v_mul_hi_i32 v7, v170, s1
	v_lshrrev_b32_e32 v8, 31, v7
	v_ashrrev_i32_e32 v7, 2, v7
	v_add_u32_e32 v7, v7, v8
	v_mul_lo_u32 v8, v7, 24
	v_sub_u32_e32 v8, v170, v8
	v_mul_lo_u32 v9, v7, s11
	v_lshl_add_u32 v162, v8, 4, v9
	v_mul_lo_u32 v9, v7, s18
	v_bitop3_b32 v7, v7, v8, 7 bitop3:0x6c
	v_lshl_add_u32 v15, v7, 4, v9
	v_add_u32_e32 v7, 0x200, v170
	v_mul_hi_i32 v8, v7, s1
	v_lshrrev_b32_e32 v9, 31, v8
	v_ashrrev_i32_e32 v8, 2, v8
	v_add_u32_e32 v8, v8, v9
	v_mul_lo_u32 v9, v8, 24
	v_sub_u32_e32 v7, v7, v9
	v_mul_lo_u32 v9, v8, s11
	v_lshl_add_u32 v164, v7, 4, v9
	v_mul_lo_u32 v9, v8, s18
	v_bitop3_b32 v7, v8, v7, 7 bitop3:0x6c
	v_lshl_add_u32 v24, v7, 4, v9
	v_add_u32_e32 v7, 0x400, v170
	v_mul_hi_i32 v8, v7, s1
	v_lshrrev_b32_e32 v9, 31, v8
	v_ashrrev_i32_e32 v8, 2, v8
	v_add_u32_e32 v8, v8, v9
	v_mul_lo_u32 v9, v8, 24
	v_sub_u32_e32 v7, v7, v9
	v_mul_lo_u32 v9, v8, s11
	v_lshlrev_b32_e32 v4, 1, v4
	v_lshl_add_u32 v166, v7, 4, v9
	v_mul_lo_u32 v9, v8, s18
	v_bitop3_b32 v7, v8, v7, 7 bitop3:0x6c
	s_ashr_i32 s1, s0, 31
	v_lshlrev_b32_e32 v6, 6, v6
	v_lshlrev_b32_e32 v3, 9, v3
	v_lshl_add_u32 v25, v7, 4, v9
	v_and_b32_e32 v7, 48, v4
	s_lshl_b64 s[16:17], s[0:1], 10
	v_or3_b32 v27, v3, v6, v7
	v_lshl_or_b32 v98, v2, 10, v4
	v_lshlrev_b32_e32 v2, 3, v171
	v_and_b32_e32 v3, 0xc0, v14
	v_lshlrev_b32_e32 v4, 1, v170
	s_add_u32 s16, s9, s16
	v_lshlrev_b32_e32 v5, 9, v5
	v_and_or_b32 v3, v2, 24, v3
	v_and_b32_e32 v4, 32, v4
	v_and_b32_e32 v2, 0x100, v2
	s_addc_u32 s17, s10, s17
	v_or3_b32 v26, v5, v6, v7
	v_or3_b32 v63, v3, v4, v2
	s_add_i32 s15, s15, 0x1800000
	global_load_dwordx4 v[2:5], v98, s[16:17]
	s_mul_hi_i32 s1, s0, 0x600
	s_add_u32 s0, s2, s15
	v_add_u32_e32 v168, 0x8000, v98
	s_addc_u32 s1, s8, s1
	global_load_dwordx4 v[6:9], v168, s[16:17]
	global_load_dwordx4 v[10:13], v162, s[0:1]
	global_load_dwordx4 v[16:19], v164, s[0:1]
	global_load_dwordx4 v[20:23], v166, s[0:1]
	v_add_u32_e32 v178, 0, v26
	s_waitcnt vmcnt(0)
	v_add_u32_e32 v179, 0, v27
	v_add_u32_e32 v180, 0, v15
	v_add_u32_e32 v181, 0, v24
	v_add_u32_e32 v182, 0, v25
	s_movk_i32 s0, 0x70
	v_bitop3_b32 v61, v62, v14, s0 bitop3:0x78
	s_movk_i32 s0, 0x80
	v_add_u32_e32 v192, v51, v61
	v_add_u32_e32 v174, s14, v63
	s_mov_b32 s11, -1
	s_waitcnt vmcnt(4)
	ds_write_b128 v178, v[2:5]
	v_mov_b32_e32 v2, 0x3000
	v_mad_u32_u24 v60, v172, s18, v2
	v_bitop3_b32 v2, v62, v55, v50 bitop3:0xde
	v_add_u32_e32 v183, 0, v2
	s_waitcnt vmcnt(3)
	ds_write_b128 v179, v[6:9]
	s_waitcnt vmcnt(2)
	ds_write_b128 v180, v[10:13] offset:32768
	s_waitcnt vmcnt(1)
	ds_write_b128 v181, v[16:19] offset:32768
	s_waitcnt vmcnt(0)
	ds_write_b128 v182, v[20:23] offset:32768
	s_waitcnt lgkmcnt(0)
	s_barrier
	ds_read_b128 v[18:21], v183 offset:32768
	ds_read_b128 v[22:25], v183 offset:45056
	ds_read_b128 v[56:59], v184 offset:32768
	ds_read_b128 v[68:71], v184 offset:45056
	s_waitcnt lgkmcnt(3)
	v_mfma_f32_32x32x16_bf16 v[34:49], v[18:21], v[128:131], 0
	v_bitop3_b32 v66, v52, v60, v50 bitop3:0xde
	v_bitop3_b32 v52, v53, v55, v50 bitop3:0xde
	v_add_u32_e32 v185, 0, v52
	v_bitop3_b32 v52, v54, v55, v50 bitop3:0xde
	v_add_u32_e32 v186, 0, v52
	v_bitop3_b32 v67, v53, v60, v50 bitop3:0xde
	v_mov_b64_e32 v[2:3], s[68:69]
	s_waitcnt lgkmcnt(2)
	v_mfma_f32_32x32x16_bf16 v[18:33], v[22:25], v[128:131], 0
	v_mov_b64_e32 v[4:5], s[70:71]
	v_mov_b64_e32 v[6:7], s[72:73]
	v_mov_b64_e32 v[8:9], s[74:75]
	v_mov_b64_e32 v[10:11], s[76:77]
	v_mov_b64_e32 v[12:13], s[78:79]
	v_mov_b64_e32 v[14:15], s[80:81]
	v_mov_b64_e32 v[16:17], s[82:83]
	s_waitcnt lgkmcnt(1)
	v_mfma_f32_32x32x16_bf16 v[34:49], v[56:59], v[124:127], v[34:49]
	ds_read_b128 v[56:59], v185 offset:32768
	s_movk_i32 s82, 0x100
	ds_read_b128 v[74:77], v192
	v_bitop3_b32 v65, v62, v60, v50 bitop3:0xde
	v_readlane_b32 s80, v254, 41
	v_readlane_b32 s74, v254, 44
	v_readlane_b32 s81, v254, 42
	s_waitcnt lgkmcnt(2)
	v_mfma_f32_32x32x16_bf16 v[18:33], v[68:71], v[124:127], v[18:33]
	ds_read_b128 v[68:71], v185 offset:45056
	v_add_u32_e32 v226, 0, v65
	v_readlane_b32 s75, v254, 45
	v_readlane_b32 s83, v254, 43
	s_movk_i32 s81, 0x300
	v_add_u32_e32 v225, 0, v66
	v_add_u32_e32 v224, 0, v67
	s_waitcnt lgkmcnt(2)
	v_mfma_f32_32x32x16_bf16 v[34:49], v[56:59], v[120:123], v[34:49]
	ds_read_b128 v[56:59], v186 offset:32768
	s_waitcnt lgkmcnt(1)
	v_mfma_f32_32x32x16_bf16 v[18:33], v[68:71], v[120:123], v[18:33]
	v_bitop3_b32 v68, v54, v60, v50 bitop3:0xde
	ds_read_b128 v[52:55], v186 offset:45056
	v_add_u32_e32 v223, 0, v68
	s_waitcnt lgkmcnt(1)
	v_mfma_f32_32x32x16_bf16 v[34:49], v[56:59], v[116:119], v[34:49]
	v_bitop3_b32 v56, v62, v50, s0 bitop3:0x36
	v_add_u32_e32 v69, v56, v60
	s_movk_i32 s0, 0xa0
	v_add_u32_e32 v222, 0, v69
	s_waitcnt lgkmcnt(0)
	v_mfma_f32_32x32x16_bf16 v[18:33], v[52:55], v[116:119], v[18:33]
	v_mad_u32_u24 v52, v172, s18, v56
	v_add_u32_e32 v187, 0, v52
	ds_read_b128 v[52:55], v187 offset:32768
	ds_read_b128 v[56:59], v187 offset:45056
	s_waitcnt lgkmcnt(0)
	v_mfma_f32_32x32x16_bf16 v[18:33], v[56:59], v[112:115], v[18:33]
	v_bitop3_b32 v56, v62, v50, s0 bitop3:0x36
	v_add_u32_e32 v70, v56, v60
	s_movk_i32 s0, 0xc0
	v_add_u32_e32 v221, 0, v70
	v_mfma_f32_32x32x16_bf16 v[34:49], v[52:55], v[112:115], v[34:49]
	v_mad_u32_u24 v52, v172, s18, v56
	v_add_u32_e32 v188, 0, v52
	ds_read_b128 v[52:55], v188 offset:32768
	ds_read_b128 v[56:59], v188 offset:45056
	s_waitcnt lgkmcnt(0)
	v_mfma_f32_32x32x16_bf16 v[18:33], v[56:59], v[108:111], v[18:33]
	v_bitop3_b32 v56, v62, v50, s0 bitop3:0x36
	v_add_u32_e32 v71, v56, v60
	s_movk_i32 s0, 0xe0
	v_add_u32_e32 v220, 0, v71
	v_mfma_f32_32x32x16_bf16 v[34:49], v[52:55], v[108:111], v[34:49]
	v_mad_u32_u24 v52, v172, s18, v56
	v_add_u32_e32 v189, 0, v52
	ds_read_b128 v[52:55], v189 offset:32768
	ds_read_b128 v[56:59], v189 offset:45056
	s_waitcnt lgkmcnt(0)
	v_mfma_f32_32x32x16_bf16 v[18:33], v[56:59], v[104:107], v[18:33]
	v_bitop3_b32 v56, v62, v50, s0 bitop3:0x36
	v_add_u32_e32 v72, v56, v60
	s_movk_i32 s0, 0x120
	v_bitop3_b32 v51, v62, v50, s0 bitop3:0x36
	s_movk_i32 s0, 0x140
	v_add_u32_e32 v219, 0, v72
	v_mfma_f32_32x32x16_bf16 v[34:49], v[52:55], v[104:107], v[34:49]
	v_mad_u32_u24 v52, v172, s18, v56
	v_add_u32_e32 v190, 0, v52
	ds_read_b128 v[52:55], v190 offset:32768
	ds_read_b128 v[56:59], v190 offset:45056
	s_waitcnt lgkmcnt(0)
	v_mfma_f32_32x32x16_bf16 v[18:33], v[56:59], v[100:103], v[18:33]
	v_bitop3_b32 v56, v62, v50, s82 bitop3:0x36
	v_add_u32_e32 v73, v56, v60
	v_add_u32_e32 v218, 0, v73
	v_mfma_f32_32x32x16_bf16 v[34:49], v[52:55], v[100:103], v[34:49]
	v_mad_u32_u24 v52, v172, s18, v56
	v_add_u32_e32 v191, 0, v52
	ds_read_b128 v[52:55], v191 offset:32768
	ds_read_b128 v[56:59], v191 offset:45056
	s_waitcnt lgkmcnt(1)
	v_mfma_f32_32x32x16_bf16 v[34:49], v[52:55], v[74:77], v[34:49]
	v_mad_u32_u24 v52, v172, s18, v51
	v_add_u32_e32 v194, 0, v52
	ds_read_b128 v[52:55], v194 offset:32768
	s_waitcnt lgkmcnt(1)
	v_mfma_f32_32x32x16_bf16 v[18:33], v[56:59], v[74:77], v[18:33]
	ds_read_b128 v[56:59], v194 offset:45056
	ds_read_b128 v[76:79], v176
	v_add_u32_e32 v74, v51, v60
	v_bitop3_b32 v51, v62, v50, s0 bitop3:0x36
	s_movk_i32 s0, 0x160
	v_bitop3_b32 v50, v62, v50, s0 bitop3:0x36
	v_add_u32_e32 v75, v51, v60
	v_add_u32_e32 v217, 0, v74
	s_waitcnt lgkmcnt(0)
	v_mfma_f32_32x32x16_bf16 v[34:49], v[52:55], v[76:79], v[34:49]
	v_mad_u32_u24 v52, v172, s18, v51
	v_add_u32_e32 v195, 0, v52
	ds_read_b128 v[52:55], v195 offset:32768
	v_mad_u32_u24 v51, v172, s18, v50
	v_add_u32_e32 v196, 0, v51
	v_add_u32_e32 v216, 0, v75
	v_mfma_f32_32x32x16_bf16 v[18:33], v[56:59], v[76:79], v[18:33]
	ds_read_b128 v[56:59], v195 offset:45056
	ds_read_b128 v[76:79], v177
	s_waitcnt lgkmcnt(0)
	v_mfma_f32_32x32x16_bf16 v[34:49], v[52:55], v[76:79], v[34:49]
	v_mfma_f32_32x32x16_bf16 v[18:33], v[56:59], v[76:79], v[18:33]
	ds_read_b128 v[54:57], v196 offset:32768
	v_add_u32_e32 v76, v50, v60
	ds_read_b128 v[50:53], v196 offset:45056
	ds_read_b128 v[58:61], v175
	v_add_u32_e32 v215, 0, v76
	s_waitcnt lgkmcnt(0)
	v_mfma_f32_32x32x16_bf16 v[34:49], v[54:57], v[58:61], v[34:49]
	v_mfma_f32_32x32x16_bf16 v[18:33], v[50:53], v[58:61], v[18:33]
	s_nop 10
	v_max_f32_e32 v50, v35, v35
	v_max_f32_e32 v51, v34, v34
	v_max_f32_e32 v50, v51, v50
	v_max3_f32 v50, v50, v36, v37
	v_max3_f32 v50, v50, v38, v39
	v_max3_f32 v50, v50, v40, v41
	v_max3_f32 v50, v50, v42, v43
	v_max3_f32 v50, v50, v44, v45
	v_max3_f32 v50, v50, v46, v47
	v_max3_f32 v50, v50, v48, v49
	v_max3_f32 v50, v50, v18, v19
	v_max3_f32 v50, v50, v20, v21
	v_max3_f32 v50, v50, v22, v23
	v_max3_f32 v50, v50, v24, v25
	v_max3_f32 v50, v50, v26, v27
	v_max3_f32 v50, v50, v28, v29
	v_max3_f32 v50, v50, v30, v31
	v_max3_f32 v50, v50, v32, v33
	v_mov_b32_e32 v51, v50
	s_nop 1
	v_permlane32_swap_b32_e32 v50, v51
	v_max_f32_e32 v51, v51, v51
	v_max_f32_e32 v50, v50, v50
	v_max_f32_e32 v50, v50, v51
	v_add_f32_e32 v51, 0x7149f2ca, v50
	v_max_f32_e32 v50, 0xf149f2ca, v50
	v_cmp_ge_f32_e32 vcc, s5, v51
	v_sub_f32_e32 v51, 0xf149f2ca, v50
	s_cmp_eq_u64 vcc, exec
	v_mul_f32_e32 v51, 0x3dd53b94, v51
	s_cselect_b64 vcc, -1, 0
	v_exp_f32_e32 v51, v51
	s_add_i32 s0, s12, 0x4040
	v_mov_b32_e32 v52, 0xf149f2ca
	s_ashr_i32 s1, s0, 31
	v_cndmask_b32_e32 v214, v50, v52, vcc
	s_lshl_b64 s[16:17], s[0:1], 10
	v_mul_f32_e32 v50, 0xbdd53b94, v214
	s_add_u32 s16, s9, s16
	v_cndmask_b32_e64 v213, v51, 1.0, vcc
	v_mov_b32_e32 v51, v50
	s_addc_u32 s17, s10, s17
	s_mul_hi_i32 s1, s0, 0x600
	s_mulk_i32 s0, 0x600
	v_fmamk_f32 v34, v34, 0x3dd53b94, v50
	v_fmamk_f32 v35, v35, 0x3dd53b94, v50
	v_fmamk_f32 v36, v36, 0x3dd53b94, v50
	v_fmamk_f32 v37, v37, 0x3dd53b94, v50
	v_fmac_f32_e32 v51, 0x3dd53b94, v49
	s_add_u32 s0, s2, s0
	v_pk_fma_f32 v[138:139], v[32:33], s[30:31], v[50:51] op_sel_hi:[1,0,0]
	v_pk_fma_f32 v[140:141], v[30:31], s[30:31], v[50:51] op_sel_hi:[1,0,0]
	v_pk_fma_f32 v[146:147], v[28:29], s[30:31], v[50:51] op_sel_hi:[1,0,0]
	v_pk_fma_f32 v[132:133], v[26:27], s[30:31], v[50:51] op_sel_hi:[1,0,0]
	v_pk_fma_f32 v[134:135], v[24:25], s[30:31], v[50:51] op_sel_hi:[1,0,0]
	v_pk_fma_f32 v[136:137], v[22:23], s[30:31], v[50:51] op_sel_hi:[1,0,0]
	v_pk_fma_f32 v[142:143], v[20:21], s[30:31], v[50:51] op_sel_hi:[1,0,0]
	v_pk_fma_f32 v[144:145], v[18:19], s[30:31], v[50:51] op_sel_hi:[1,0,0]
	v_exp_f32_e32 v153, v34
	v_exp_f32_e32 v154, v35
	v_exp_f32_e32 v230, v36
	v_exp_f32_e32 v231, v37
	s_addc_u32 s1, s8, s1
	global_load_dwordx4 v[18:21], v98, s[16:17]
	global_load_dwordx4 v[22:25], v168, s[16:17]
	global_load_dwordx4 v[26:29], v162, s[0:1]
	global_load_dwordx4 v[30:33], v164, s[0:1]
	global_load_dwordx4 v[34:37], v166, s[0:1]
	v_fmamk_f32 v38, v38, 0x3dd53b94, v50
	v_fmamk_f32 v39, v39, 0x3dd53b94, v50
	v_fmamk_f32 v40, v40, 0x3dd53b94, v50
	v_fmamk_f32 v41, v41, 0x3dd53b94, v50
	v_fmamk_f32 v42, v42, 0x3dd53b94, v50
	v_fmamk_f32 v43, v43, 0x3dd53b94, v50
	v_fmamk_f32 v44, v44, 0x3dd53b94, v50
	v_fmamk_f32 v45, v45, 0x3dd53b94, v50
	v_fmamk_f32 v46, v46, 0x3dd53b94, v50
	v_fmamk_f32 v47, v47, 0x3dd53b94, v50
	v_fmamk_f32 v48, v48, 0x3dd53b94, v50
	v_exp_f32_e32 v232, v38
	v_exp_f32_e32 v233, v39
	v_exp_f32_e32 v155, v40
	v_exp_f32_e32 v229, v41
	v_exp_f32_e32 v151, v42
	v_exp_f32_e32 v156, v43
	v_exp_f32_e32 v157, v44
	v_exp_f32_e32 v158, v45
	v_exp_f32_e32 v148, v46
	v_exp_f32_e32 v149, v47
	v_exp_f32_e32 v150, v48
	v_exp_f32_e32 v159, v51
	s_waitcnt vmcnt(0)
	s_addk_i32 s14, 0x4000
	s_waitcnt vmcnt(4)
	ds_write_b128 v178, v[18:21] offset:16384
	s_waitcnt vmcnt(3)
	ds_write_b128 v179, v[22:25] offset:16384
	s_waitcnt vmcnt(2)
	ds_write_b128 v180, v[26:29] offset:57344
	s_waitcnt vmcnt(1)
	ds_write_b128 v181, v[30:33] offset:57344
	s_waitcnt vmcnt(0)
	ds_write_b128 v182, v[34:37] offset:57344
	s_mov_b32 s100, 0xaaaaaaab
	v_lshrrev_b32_e32 v38, 6, v0
	v_lshl_add_u32 v39, v38, 7, v0
	v_mul_hi_u32 v40, v39, s100
	v_lshrrev_b32_e32 v40, 4, v40
	v_mul_u32_u24_e32 v41, 24, v40
	v_sub_u32_e32 v41, v39, v41
	v_and_b32_e32 v42, 7, v40
	v_xor_b32_e32 v41, v41, v42
	v_mul_u32_u24_e32 v42, 0x600, v40
	v_lshl_add_u32 v180, v41, 4, v42
	v_add_u32_e32 v39, 64, v39
	v_mul_hi_u32 v40, v39, s100
	v_lshrrev_b32_e32 v40, 4, v40
	v_mul_u32_u24_e32 v41, 24, v40
	v_sub_u32_e32 v41, v39, v41
	v_and_b32_e32 v42, 7, v40
	v_xor_b32_e32 v41, v41, v42
	v_mul_u32_u24_e32 v42, 0x600, v40
	v_lshl_add_u32 v181, v41, 4, v42
	v_add_u32_e32 v39, 64, v39
	v_mul_hi_u32 v40, v39, s100
	v_lshrrev_b32_e32 v40, 4, v40
	v_mul_u32_u24_e32 v41, 24, v40
	v_sub_u32_e32 v41, v39, v41
	v_and_b32_e32 v42, 7, v40
	v_xor_b32_e32 v41, v41, v42
	v_mul_u32_u24_e32 v42, 0x600, v40
	v_lshl_add_u32 v182, v41, 4, v42
	v_lshl_add_u32 v39, v38, 6, v0
	v_and_b32_e32 v40, 3, v39
	v_lshlrev_b32_e32 v40, 4, v40
	v_bfe_u32 v41, v39, 5, 2
	v_lshl_or_b32 v40, v41, 6, v40
	v_bfe_u32 v41, v39, 2, 2
	v_lshl_or_b32 v40, v41, 10, v40
	v_bfe_u32 v41, v39, 7, 1
	v_lshl_or_b32 v40, v41, 12, v40
	v_bfe_u32 v41, v39, 4, 1
	v_lshl_or_b32 v40, v41, 13, v40
	v_bfe_u32 v41, v39, 8, 2
	v_lshl_or_b32 v178, v41, 14, v40
	v_add_u32_e32 v39, 64, v39
	v_and_b32_e32 v40, 3, v39
	v_lshlrev_b32_e32 v40, 4, v40
	v_bfe_u32 v41, v39, 5, 2
	v_lshl_or_b32 v40, v41, 6, v40
	v_bfe_u32 v41, v39, 2, 2
	v_lshl_or_b32 v40, v41, 10, v40
	v_bfe_u32 v41, v39, 7, 1
	v_lshl_or_b32 v40, v41, 12, v40
	v_bfe_u32 v41, v39, 4, 1
	v_lshl_or_b32 v40, v41, 13, v40
	v_bfe_u32 v41, v39, 8, 2
	v_lshl_or_b32 v179, v41, 14, v40
	v_readfirstlane_b32 s100, v38
	s_nop 1
	s_mul_i32 s101, s100, 0xc00
	s_lshl_b32 s100, s100, 11
	v_add_u32_e32 v199, s14, v63
	v_mov_b64_e32 v[64:65], v[16:17]
	v_mov_b64_e32 v[48:49], v[16:17]
	v_mov_b64_e32 v[32:33], v[16:17]
	s_addk_i32 s12, 0x4080
	s_sub_i32 s13, s13, 64
	v_mov_b64_e32 v[62:63], v[14:15]
	v_mov_b64_e32 v[60:61], v[12:13]
	v_mov_b64_e32 v[58:59], v[10:11]
	v_mov_b64_e32 v[56:57], v[8:9]
	v_mov_b64_e32 v[54:55], v[6:7]
	v_mov_b64_e32 v[52:53], v[4:5]
	v_mov_b64_e32 v[50:51], v[2:3]
	v_mov_b64_e32 v[46:47], v[14:15]
	v_mov_b64_e32 v[44:45], v[12:13]
	v_mov_b64_e32 v[42:43], v[10:11]
	v_mov_b64_e32 v[40:41], v[8:9]
	v_mov_b64_e32 v[38:39], v[6:7]
	v_mov_b64_e32 v[36:37], v[4:5]
	v_mov_b64_e32 v[34:35], v[2:3]
	v_mov_b64_e32 v[30:31], v[14:15]
	v_mov_b64_e32 v[28:29], v[12:13]
	v_mov_b64_e32 v[26:27], v[10:11]
	v_mov_b64_e32 v[24:25], v[8:9]
	v_mov_b64_e32 v[22:23], v[6:7]
	v_mov_b64_e32 v[20:21], v[4:5]
	v_mov_b64_e32 v[18:19], v[2:3]
	s_waitcnt lgkmcnt(0)
	s_barrier
.LBB0_855:
	s_add_i32 s11, s11, 2
	s_sub_i32 s0, s13, 64
	s_cmp_lt_u32 s11, 3
	s_cselect_b32 s0, s12, s0
	s_ashr_i32 s1, s0, 31
	s_lshl_b64 s[14:15], s[0:1], 10
	s_add_u32 s14, s9, s14
	s_addc_u32 s15, s10, s15
	s_mul_hi_i32 s1, s0, 0x600
	s_mulk_i32 s0, 0x600
	s_add_u32 s0, s2, s0
	s_addc_u32 s1, s8, s1
	s_add_i32 m0, s101, 0x8000
	s_nop 0
	global_load_lds_dwordx4 v180, s[0:1]
	s_add_i32 m0, s101, 0x8400
	s_nop 0
	global_load_lds_dwordx4 v181, s[0:1]
	s_add_i32 m0, s101, 0x8800
	s_nop 0
	global_load_lds_dwordx4 v182, s[0:1]
	ds_read_b128 v[66:69], v183 offset:57344
	ds_read_b128 v[70:73], v226 offset:57344
	ds_read_b128 v[234:237], v184 offset:57344
	ds_read_b128 v[238:241], v225 offset:57344
	v_add_f32_e32 v152, 0, v153
	v_add_f32_e32 v152, v154, v152
	s_waitcnt lgkmcnt(3)
	v_mfma_f32_32x32x16_bf16 v[82:97], v[66:69], v[128:131], 0
	v_add_f32_e32 v152, v230, v152
	v_add_f32_e32 v152, v231, v152
	v_add_f32_e32 v152, v232, v152
	v_add_f32_e32 v152, v233, v152
	v_add_f32_e32 v152, v155, v152
	v_add_f32_e32 v152, v229, v152
	v_add_f32_e32 v152, v151, v152
	s_waitcnt lgkmcnt(2)
	v_mfma_f32_32x32x16_bf16 v[66:81], v[70:73], v[128:131], 0
	v_add_f32_e32 v152, v156, v152
	v_add_f32_e32 v152, v157, v152
	v_add_f32_e32 v152, v158, v152
	v_exp_f32_e32 v144, v144
	v_add_f32_e32 v152, v148, v152
	v_exp_f32_e32 v145, v145
	v_add_f32_e32 v152, v149, v152
	s_waitcnt lgkmcnt(1)
	v_mfma_f32_32x32x16_bf16 v[82:97], v[234:237], v[124:127], v[82:97]
	v_exp_f32_e32 v142, v142
	v_add_f32_e32 v152, v150, v152
	v_exp_f32_e32 v143, v143
	v_add_f32_e32 v152, v159, v152
	v_exp_f32_e32 v136, v136
	v_add_f32_e32 v152, v144, v152
	v_exp_f32_e32 v137, v137
	s_waitcnt lgkmcnt(0)
	v_mfma_f32_32x32x16_bf16 v[66:81], v[238:241], v[124:127], v[66:81]
	ds_read_b128 v[234:237], v185 offset:57344
	ds_read_b128 v[238:241], v224 offset:57344
	v_add_f32_e32 v152, v145, v152
	v_exp_f32_e32 v134, v134
	v_add_f32_e32 v152, v142, v152
	v_exp_f32_e32 v135, v135
	v_add_f32_e32 v152, v143, v152
	v_exp_f32_e32 v132, v132
	s_waitcnt lgkmcnt(1)
	v_mfma_f32_32x32x16_bf16 v[82:97], v[234:237], v[120:123], v[82:97]
	v_add_f32_e32 v152, v136, v152
	v_exp_f32_e32 v133, v133
	v_add_f32_e32 v152, v137, v152
	v_exp_f32_e32 v146, v146
	v_add_f32_e32 v152, v134, v152
	v_exp_f32_e32 v147, v147
	v_add_f32_e32 v152, v135, v152
	s_waitcnt lgkmcnt(0)
	v_mfma_f32_32x32x16_bf16 v[66:81], v[238:241], v[120:123], v[66:81]
	ds_read_b128 v[234:237], v186 offset:57344
	ds_read_b128 v[238:241], v223 offset:57344
	v_exp_f32_e32 v140, v140
	v_add_f32_e32 v152, v132, v152
	v_exp_f32_e32 v141, v141
	v_add_f32_e32 v152, v133, v152
	v_exp_f32_e32 v138, v138
	v_add_f32_e32 v152, v146, v152
	s_waitcnt lgkmcnt(1)
	v_mfma_f32_32x32x16_bf16 v[82:97], v[234:237], v[116:119], v[82:97]
	v_exp_f32_e32 v139, v139
	v_add_f32_e32 v152, v147, v152
	v_add_f32_e32 v152, v140, v152
	v_add_f32_e32 v152, v141, v152
	v_add_f32_e32 v152, v138, v152
	v_add_f32_e32 v227, v139, v152
	v_mov_b32_e32 v228, v227
	s_waitcnt lgkmcnt(0)
	v_mfma_f32_32x32x16_bf16 v[66:81], v[238:241], v[116:119], v[66:81]
	ds_read_b128 v[234:237], v187 offset:57344
	ds_read_b128 v[238:241], v222 offset:57344
	v_cvt_pk_bf16_f32 v152, v153, v154
	v_cvt_pk_bf16_f32 v154, v232, v233
	v_permlane32_swap_b32_e32 v227, v228
	v_cvt_pk_bf16_f32 v153, v230, v231
	v_cvt_pk_bf16_f32 v155, v155, v229
	s_waitcnt lgkmcnt(1)
	v_mfma_f32_32x32x16_bf16 v[82:97], v[234:237], v[112:115], v[82:97]
	v_permlane32_swap_b32_e32 v152, v154
	v_cvt_pk_bf16_f32 v156, v151, v156
	v_cvt_pk_bf16_f32 v157, v157, v158
	v_cvt_pk_bf16_f32 v158, v148, v149
	v_cvt_pk_bf16_f32 v159, v150, v159
	v_cvt_pk_bf16_f32 v230, v144, v145
	s_waitcnt lgkmcnt(0)
	v_mfma_f32_32x32x16_bf16 v[66:81], v[238:241], v[112:115], v[66:81]
	ds_read_b128 v[234:237], v188 offset:57344
	ds_read_b128 v[238:241], v221 offset:57344
	v_cvt_pk_bf16_f32 v231, v142, v143
	v_cvt_pk_bf16_f32 v232, v136, v137
	v_cvt_pk_bf16_f32 v233, v134, v135
	v_permlane32_swap_b32_e32 v153, v155
	v_permlane32_swap_b32_e32 v156, v158
	s_waitcnt lgkmcnt(1)
	v_mfma_f32_32x32x16_bf16 v[82:97], v[234:237], v[108:111], v[82:97]
	v_permlane32_swap_b32_e32 v157, v159
	v_permlane32_swap_b32_e32 v230, v232
	v_permlane32_swap_b32_e32 v231, v233
	s_waitcnt lgkmcnt(0)
	v_mfma_f32_32x32x16_bf16 v[66:81], v[238:241], v[108:111], v[66:81]
	ds_read_b128 v[234:237], v189 offset:57344
	ds_read_b128 v[238:241], v220 offset:57344
	s_waitcnt lgkmcnt(1)
	v_mfma_f32_32x32x16_bf16 v[82:97], v[234:237], v[104:107], v[82:97]
	s_waitcnt lgkmcnt(0)
	v_mfma_f32_32x32x16_bf16 v[66:81], v[238:241], v[104:107], v[66:81]
	ds_read_b128 v[234:237], v190 offset:57344
	ds_read_b128 v[238:241], v219 offset:57344
	s_waitcnt lgkmcnt(1)
	v_mfma_f32_32x32x16_bf16 v[82:97], v[234:237], v[100:103], v[82:97]
	s_waitcnt lgkmcnt(0)
	v_mfma_f32_32x32x16_bf16 v[66:81], v[238:241], v[100:103], v[66:81]
	ds_read_b128 v[234:237], v191 offset:57344
	ds_read_b128 v[238:241], v218 offset:57344
	ds_read_b128 v[242:245], v192
	s_waitcnt lgkmcnt(0)
	v_mfma_f32_32x32x16_bf16 v[82:97], v[234:237], v[242:245], v[82:97]
	v_mfma_f32_32x32x16_bf16 v[66:81], v[238:241], v[242:245], v[66:81]
	ds_read_b128 v[234:237], v194 offset:57344
	ds_read_b128 v[238:241], v217 offset:57344
	ds_read_b128 v[242:245], v176
	s_waitcnt lgkmcnt(0)
	v_mfma_f32_32x32x16_bf16 v[82:97], v[234:237], v[242:245], v[82:97]
	v_mfma_f32_32x32x16_bf16 v[66:81], v[238:241], v[242:245], v[66:81]
	ds_read_b128 v[234:237], v195 offset:57344
	ds_read_b128 v[238:241], v216 offset:57344
	ds_read_b128 v[242:245], v177
	s_waitcnt lgkmcnt(0)
	v_mfma_f32_32x32x16_bf16 v[82:97], v[234:237], v[242:245], v[82:97]
	v_mfma_f32_32x32x16_bf16 v[66:81], v[238:241], v[242:245], v[66:81]
	ds_read_b128 v[234:237], v196 offset:57344
	ds_read_b128 v[238:241], v215 offset:57344
	ds_read_b128 v[242:245], v175
	s_waitcnt lgkmcnt(0)
	v_mfma_f32_32x32x16_bf16 v[82:97], v[234:237], v[242:245], v[82:97]
	v_cvt_pk_bf16_f32 v234, v132, v133
	v_cvt_pk_bf16_f32 v236, v140, v141
	v_cvt_pk_bf16_f32 v235, v146, v147
	v_cvt_pk_bf16_f32 v237, v138, v139
	v_permlane32_swap_b32_e32 v234, v236
	s_nop 0
	v_permlane32_swap_b32_e32 v235, v237
	v_mfma_f32_32x32x16_bf16 v[66:81], v[238:241], v[242:245], v[66:81]
	ds_read_b64_tr_b16 v[238:239], v174 offset:0
	ds_read_b64_tr_b16 v[240:241], v174 offset:0x800
	ds_read_b64_tr_b16 v[242:243], v174 offset:0x1000
	ds_read_b64_tr_b16 v[244:245], v174 offset:0x1800
	ds_read_b64_tr_b16 v[246:247], v174 offset:0x2000
	ds_read_b64_tr_b16 v[248:249], v174 offset:0x2800
	ds_read_b64_tr_b16 v[204:205], v174 offset:0x3000
	ds_read_b64_tr_b16 v[206:207], v174 offset:0x3800
	s_waitcnt lgkmcnt(0)
	s_nop 0
	v_mfma_f32_32x32x16_bf16 v[2:17], v[152:155], v[238:241], v[2:17]
	v_mfma_f32_32x32x16_bf16 v[2:17], v[156:159], v[242:245], v[2:17]
	v_mfma_f32_32x32x16_bf16 v[2:17], v[230:233], v[246:249], v[2:17]
	v_mfma_f32_32x32x16_bf16 v[2:17], v[234:237], v[204:207], v[2:17]
	ds_read_b64_tr_b16 v[204:205], v174 offset:0x200
	ds_read_b64_tr_b16 v[206:207], v174 offset:0xa00
	ds_read_b64_tr_b16 v[238:239], v174 offset:0x1200
	ds_read_b64_tr_b16 v[240:241], v174 offset:0x1a00
	ds_read_b64_tr_b16 v[242:243], v174 offset:0x2200
	ds_read_b64_tr_b16 v[244:245], v174 offset:0x2a00
	ds_read_b64_tr_b16 v[246:247], v174 offset:0x3200
	ds_read_b64_tr_b16 v[248:249], v174 offset:0x3a00
	s_waitcnt lgkmcnt(0)
	s_nop 0
	v_mfma_f32_32x32x16_bf16 v[50:65], v[152:155], v[204:207], v[50:65]
	ds_read_b64_tr_b16 v[204:205], v174 offset:0x400
	ds_read_b64_tr_b16 v[206:207], v174 offset:0xc00
	v_mfma_f32_32x32x16_bf16 v[50:65], v[156:159], v[238:241], v[50:65]
	ds_read_b64_tr_b16 v[238:239], v174 offset:0x1400
	ds_read_b64_tr_b16 v[240:241], v174 offset:0x1c00
	v_mfma_f32_32x32x16_bf16 v[50:65], v[230:233], v[242:245], v[50:65]
	ds_read_b64_tr_b16 v[242:243], v174 offset:0x2400
	ds_read_b64_tr_b16 v[244:245], v174 offset:0x2c00
	v_mfma_f32_32x32x16_bf16 v[50:65], v[234:237], v[246:249], v[50:65]
	ds_read_b64_tr_b16 v[246:247], v174 offset:0x3400
	ds_read_b64_tr_b16 v[248:249], v174 offset:0x3c00
	s_waitcnt lgkmcnt(0)
	v_mfma_f32_32x32x16_bf16 v[34:49], v[152:155], v[204:207], v[34:49]
	ds_read_b64_tr_b16 v[204:205], v174 offset:0x600
	ds_read_b64_tr_b16 v[206:207], v174 offset:0xe00
	v_mfma_f32_32x32x16_bf16 v[34:49], v[156:159], v[238:241], v[34:49]
	ds_read_b64_tr_b16 v[238:239], v174 offset:0x1600
	ds_read_b64_tr_b16 v[240:241], v174 offset:0x1e00
	v_mfma_f32_32x32x16_bf16 v[34:49], v[230:233], v[242:245], v[34:49]
	ds_read_b64_tr_b16 v[242:243], v174 offset:0x2600
	ds_read_b64_tr_b16 v[244:245], v174 offset:0x2e00
	v_mfma_f32_32x32x16_bf16 v[34:49], v[234:237], v[246:249], v[34:49]
	ds_read_b64_tr_b16 v[246:247], v174 offset:0x3600
	ds_read_b64_tr_b16 v[248:249], v174 offset:0x3e00
	s_waitcnt lgkmcnt(0)
	v_mfma_f32_32x32x16_bf16 v[18:33], v[152:155], v[204:207], v[18:33]
	v_max_f32_e32 v152, v83, v83
	v_max_f32_e32 v153, v82, v82
	v_max_f32_e32 v152, v153, v152
	v_max3_f32 v152, v152, v84, v85
	v_max3_f32 v152, v152, v86, v87
	v_max3_f32 v152, v152, v88, v89
	v_max3_f32 v152, v152, v90, v91
	v_max3_f32 v152, v152, v92, v93
	v_max3_f32 v152, v152, v94, v95
	v_mfma_f32_32x32x16_bf16 v[18:33], v[156:159], v[238:241], v[18:33]
	v_max3_f32 v152, v152, v96, v97
	v_max3_f32 v152, v152, v66, v67
	v_max3_f32 v152, v152, v68, v69
	v_max3_f32 v152, v152, v70, v71
	v_max3_f32 v152, v152, v72, v73
	v_max3_f32 v152, v152, v74, v75
	v_max3_f32 v152, v152, v76, v77
	v_max3_f32 v152, v152, v78, v79
	v_mfma_f32_32x32x16_bf16 v[18:33], v[230:233], v[242:245], v[18:33]
	v_max3_f32 v152, v152, v80, v81
	v_mov_b32_e32 v153, v152
	s_nop 1
	v_permlane32_swap_b32_e32 v152, v153
	v_max_f32_e32 v153, v153, v153
	v_max_f32_e32 v152, v152, v152
	v_max_f32_e32 v152, v152, v153
	v_sub_f32_e32 v153, v152, v214
	v_cmp_ge_f32_e32 vcc, s5, v153
	v_max_f32_e32 v153, v214, v214
	v_max_f32_e32 v152, v153, v152
	v_mfma_f32_32x32x16_bf16 v[18:33], v[234:237], v[246:249], v[18:33]
	v_sub_f32_e32 v153, v214, v152
	v_mul_f32_e32 v153, 0x3dd53b94, v153
	v_exp_f32_e32 v153, v153
	s_cmp_eq_u64 vcc, exec
	s_cselect_b64 s[40:41], -1, 0
	s_barrier
	s_mov_b32 m0, s100
	v_cndmask_b32_e64 v234, v153, 1.0, s[40:41]
	global_load_lds_dwordx4 v178, s[14:15]
	s_add_i32 m0, s100, 0x400
	v_cmp_gt_f32_e32 vcc, 1.0, v234
	global_load_lds_dwordx4 v179, s[14:15]
	s_cbranch_vccz .LBB0_859
	s_and_saveexec_b64 s[0:1], s[38:39]
	ds_write_b32 v197, v234 offset:128
	s_or_b64 exec, exec, s[0:1]
	s_waitcnt lgkmcnt(0)
	ds_read_b128 v[132:135], v193 offset:224
	ds_read_b128 v[136:139], v193 offset:192
	ds_read_b128 v[140:143], v193 offset:160
	ds_read_b128 v[144:147], v193 offset:128
	s_waitcnt lgkmcnt(3)
	v_pk_mul_f32 v[16:17], v[16:17], v[134:135]
	s_waitcnt lgkmcnt(2)
	v_pk_mul_f32 v[12:13], v[12:13], v[138:139]
	s_waitcnt lgkmcnt(1)
	v_pk_mul_f32 v[8:9], v[8:9], v[142:143]
	s_waitcnt lgkmcnt(0)
	v_pk_mul_f32 v[4:5], v[4:5], v[146:147]
	v_pk_mul_f32 v[14:15], v[14:15], v[132:133]
	v_pk_mul_f32 v[10:11], v[10:11], v[136:137]
	v_pk_mul_f32 v[6:7], v[6:7], v[140:141]
	v_pk_mul_f32 v[2:3], v[2:3], v[144:145]
	v_pk_mul_f32 v[64:65], v[64:65], v[134:135]
	v_pk_mul_f32 v[60:61], v[60:61], v[138:139]
	v_pk_mul_f32 v[56:57], v[56:57], v[142:143]
	v_pk_mul_f32 v[52:53], v[52:53], v[146:147]
	v_pk_mul_f32 v[62:63], v[62:63], v[132:133]
	v_pk_mul_f32 v[58:59], v[58:59], v[136:137]
	v_pk_mul_f32 v[54:55], v[54:55], v[140:141]
	v_pk_mul_f32 v[50:51], v[50:51], v[144:145]
	v_pk_mul_f32 v[48:49], v[48:49], v[134:135]
	v_pk_mul_f32 v[44:45], v[44:45], v[138:139]
	v_pk_mul_f32 v[40:41], v[40:41], v[142:143]
	v_pk_mul_f32 v[36:37], v[36:37], v[146:147]
	v_pk_mul_f32 v[46:47], v[46:47], v[132:133]
	v_pk_mul_f32 v[42:43], v[42:43], v[136:137]
	v_pk_mul_f32 v[38:39], v[38:39], v[140:141]
	v_pk_mul_f32 v[34:35], v[34:35], v[144:145]
	v_pk_mul_f32 v[32:33], v[32:33], v[134:135]
	v_pk_mul_f32 v[28:29], v[28:29], v[138:139]
	v_pk_mul_f32 v[24:25], v[24:25], v[142:143]
	v_pk_mul_f32 v[20:21], v[20:21], v[146:147]
	v_pk_mul_f32 v[30:31], v[30:31], v[132:133]
	v_pk_mul_f32 v[26:27], v[26:27], v[136:137]
	v_pk_mul_f32 v[22:23], v[22:23], v[140:141]
	v_pk_mul_f32 v[18:19], v[18:19], v[144:145]
.LBB0_859:
	v_cndmask_b32_e64 v214, v152, v214, s[40:41]
	v_mul_f32_e32 v148, 0xbdd53b94, v214
	v_fmamk_f32 v82, v82, 0x3dd53b94, v148
	v_fmamk_f32 v83, v83, 0x3dd53b94, v148
	v_fmamk_f32 v84, v84, 0x3dd53b94, v148
	v_fmamk_f32 v85, v85, 0x3dd53b94, v148
	v_fmamk_f32 v86, v86, 0x3dd53b94, v148
	v_fmamk_f32 v87, v87, 0x3dd53b94, v148
	v_fmamk_f32 v88, v88, 0x3dd53b94, v148
	v_fmamk_f32 v89, v89, 0x3dd53b94, v148
	v_fmamk_f32 v90, v90, 0x3dd53b94, v148
	v_fmamk_f32 v91, v91, 0x3dd53b94, v148
	v_fmamk_f32 v92, v92, 0x3dd53b94, v148
	v_fmamk_f32 v93, v93, 0x3dd53b94, v148
	v_fmamk_f32 v94, v94, 0x3dd53b94, v148
	v_fmamk_f32 v95, v95, 0x3dd53b94, v148
	v_fmamk_f32 v96, v96, 0x3dd53b94, v148
	v_fmamk_f32 v97, v97, 0x3dd53b94, v148
	v_fmamk_f32 v152, v73, 0x3dd53b94, v148
	v_fmamk_f32 v153, v74, 0x3dd53b94, v148
	v_fmamk_f32 v157, v66, 0x3dd53b94, v148
	v_fmamk_f32 v158, v67, 0x3dd53b94, v148
	v_fmamk_f32 v159, v68, 0x3dd53b94, v148
	v_fmamk_f32 v229, v69, 0x3dd53b94, v148
	v_fmamk_f32 v230, v70, 0x3dd53b94, v148
	v_fmamk_f32 v150, v71, 0x3dd53b94, v148
	v_fmamk_f32 v151, v72, 0x3dd53b94, v148
	v_fmamk_f32 v154, v75, 0x3dd53b94, v148
	v_fmamk_f32 v155, v76, 0x3dd53b94, v148
	v_fmamk_f32 v156, v77, 0x3dd53b94, v148
	v_fmamk_f32 v149, v78, 0x3dd53b94, v148
	v_exp_f32_e32 v141, v82
	v_exp_f32_e32 v143, v83
	v_exp_f32_e32 v144, v84
	v_exp_f32_e32 v145, v85
	v_exp_f32_e32 v146, v86
	v_exp_f32_e32 v147, v87
	v_exp_f32_e32 v140, v88
	v_exp_f32_e32 v142, v89
	v_exp_f32_e32 v135, v90
	v_exp_f32_e32 v137, v91
	v_exp_f32_e32 v138, v92
	v_exp_f32_e32 v139, v93
	v_exp_f32_e32 v132, v94
	v_exp_f32_e32 v133, v95
	v_exp_f32_e32 v134, v96
	v_exp_f32_e32 v136, v97
	v_fmamk_f32 v231, v79, 0x3dd53b94, v148
	v_fmamk_f32 v232, v80, 0x3dd53b94, v148
	v_fmac_f32_e32 v148, 0x3dd53b94, v81
	s_waitcnt vmcnt(2) lgkmcnt(0)
	s_barrier
	s_add_i32 s0, s12, 64
	s_cmp_lt_u32 s11, 2
	s_cselect_b32 s0, s0, s13
	s_ashr_i32 s1, s0, 31
	s_lshl_b64 s[14:15], s[0:1], 10
	s_add_u32 s14, s9, s14
	s_addc_u32 s15, s10, s15
	s_mul_hi_i32 s1, s0, 0x600
	s_mulk_i32 s0, 0x600
	s_add_u32 s0, s2, s0
	s_addc_u32 s1, s8, s1
	s_add_i32 m0, s101, 0xe000
	s_nop 0
	global_load_lds_dwordx4 v180, s[0:1]
	s_add_i32 m0, s101, 0xe400
	s_nop 0
	global_load_lds_dwordx4 v181, s[0:1]
	s_add_i32 m0, s101, 0xe800
	s_nop 0
	global_load_lds_dwordx4 v182, s[0:1]
	ds_read_b128 v[66:69], v183 offset:32768
	ds_read_b128 v[70:73], v183 offset:45056
	ds_read_b128 v[204:207], v184 offset:32768
	ds_read_b128 v[236:239], v184 offset:45056
	v_exp_f32_e32 v209, v152
	v_add_f32_e32 v152, 0, v141
	s_waitcnt lgkmcnt(3)
	v_mfma_f32_32x32x16_bf16 v[82:97], v[66:69], v[128:131], 0
	v_add_f32_e32 v152, v143, v152
	v_add_f32_e32 v152, v144, v152
	v_add_f32_e32 v152, v145, v152
	v_add_f32_e32 v152, v146, v152
	v_add_f32_e32 v152, v147, v152
	v_add_f32_e32 v152, v140, v152
	v_add_f32_e32 v152, v142, v152
	s_waitcnt lgkmcnt(2)
	v_mfma_f32_32x32x16_bf16 v[66:81], v[70:73], v[128:131], 0
	v_add_f32_e32 v152, v135, v152
	v_add_f32_e32 v152, v137, v152
	v_add_f32_e32 v152, v138, v152
	v_add_f32_e32 v152, v139, v152
	v_add_f32_e32 v152, v132, v152
	v_add_f32_e32 v152, v133, v152
	v_add_f32_e32 v152, v134, v152
	s_waitcnt lgkmcnt(1)
	v_mfma_f32_32x32x16_bf16 v[82:97], v[204:207], v[124:127], v[82:97]
	v_add_f32_e32 v152, v136, v152
	v_exp_f32_e32 v208, v230
	v_exp_f32_e32 v150, v150
	v_exp_f32_e32 v151, v151
	v_exp_f32_e32 v210, v153
	v_exp_f32_e32 v211, v154
	v_exp_f32_e32 v233, v156
	s_waitcnt lgkmcnt(0)
	v_mfma_f32_32x32x16_bf16 v[66:81], v[236:239], v[124:127], v[66:81]
	ds_read_b128 v[204:207], v185 offset:32768
	ds_read_b128 v[236:239], v185 offset:45056
	v_exp_f32_e32 v149, v149
	v_exp_f32_e32 v148, v148
	v_cvt_pk_bf16_f32 v153, v144, v145
	v_cvt_pk_bf16_f32 v154, v146, v147
	v_cvt_pk_bf16_f32 v156, v135, v137
	v_cvt_pk_bf16_f32 v230, v210, v211
	s_waitcnt lgkmcnt(1)
	v_mfma_f32_32x32x16_bf16 v[82:97], v[204:207], v[120:123], v[82:97]
	s_waitcnt lgkmcnt(0)
	v_mfma_f32_32x32x16_bf16 v[66:81], v[236:239], v[120:123], v[66:81]
	ds_read_b128 v[204:207], v186 offset:32768
	ds_read_b128 v[236:239], v186 offset:45056
	s_waitcnt lgkmcnt(1)
	v_mfma_f32_32x32x16_bf16 v[82:97], v[204:207], v[116:119], v[82:97]
	s_waitcnt lgkmcnt(0)
	v_mfma_f32_32x32x16_bf16 v[66:81], v[236:239], v[116:119], v[66:81]
	ds_read_b128 v[204:207], v187 offset:32768
	ds_read_b128 v[236:239], v187 offset:45056
	s_waitcnt lgkmcnt(1)
	v_mfma_f32_32x32x16_bf16 v[82:97], v[204:207], v[112:115], v[82:97]
	s_waitcnt lgkmcnt(0)
	v_mfma_f32_32x32x16_bf16 v[66:81], v[236:239], v[112:115], v[66:81]
	ds_read_b128 v[204:207], v188 offset:32768
	ds_read_b128 v[236:239], v188 offset:45056
	s_waitcnt lgkmcnt(1)
	v_mfma_f32_32x32x16_bf16 v[82:97], v[204:207], v[108:111], v[82:97]
	s_waitcnt lgkmcnt(0)
	v_mfma_f32_32x32x16_bf16 v[66:81], v[236:239], v[108:111], v[66:81]
	ds_read_b128 v[204:207], v189 offset:32768
	ds_read_b128 v[236:239], v189 offset:45056
	s_waitcnt lgkmcnt(1)
	v_mfma_f32_32x32x16_bf16 v[82:97], v[204:207], v[104:107], v[82:97]
	s_waitcnt lgkmcnt(0)
	v_mfma_f32_32x32x16_bf16 v[66:81], v[236:239], v[104:107], v[66:81]
	ds_read_b128 v[204:207], v190 offset:32768
	ds_read_b128 v[236:239], v190 offset:45056
	s_waitcnt lgkmcnt(1)
	v_mfma_f32_32x32x16_bf16 v[82:97], v[204:207], v[100:103], v[82:97]
	s_waitcnt lgkmcnt(0)
	v_mfma_f32_32x32x16_bf16 v[66:81], v[236:239], v[100:103], v[66:81]
	ds_read_b128 v[204:207], v191 offset:32768
	ds_read_b128 v[236:239], v191 offset:45056
	ds_read_b128 v[240:243], v192
	s_waitcnt lgkmcnt(0)
	v_mfma_f32_32x32x16_bf16 v[82:97], v[204:207], v[240:243], v[82:97]
	v_mfma_f32_32x32x16_bf16 v[66:81], v[236:239], v[240:243], v[66:81]
	ds_read_b128 v[204:207], v194 offset:32768
	ds_read_b128 v[236:239], v194 offset:45056
	ds_read_b128 v[240:243], v176
	s_waitcnt lgkmcnt(0)
	v_mfma_f32_32x32x16_bf16 v[82:97], v[204:207], v[240:243], v[82:97]
	v_mfma_f32_32x32x16_bf16 v[66:81], v[236:239], v[240:243], v[66:81]
	ds_read_b128 v[204:207], v195 offset:32768
	ds_read_b128 v[236:239], v195 offset:45056
	ds_read_b128 v[240:243], v177
	s_waitcnt lgkmcnt(0)
	v_mfma_f32_32x32x16_bf16 v[82:97], v[204:207], v[240:243], v[82:97]
	v_mfma_f32_32x32x16_bf16 v[66:81], v[236:239], v[240:243], v[66:81]
	ds_read_b128 v[204:207], v196 offset:32768
	ds_read_b128 v[236:239], v196 offset:45056
	ds_read_b128 v[240:243], v175
	s_waitcnt lgkmcnt(0)
	v_mfma_f32_32x32x16_bf16 v[82:97], v[204:207], v[240:243], v[82:97]
	v_exp_f32_e32 v204, v157
	v_exp_f32_e32 v205, v158
	v_exp_f32_e32 v206, v159
	v_exp_f32_e32 v207, v229
	v_add_f32_e32 v152, v204, v152
	v_add_f32_e32 v152, v205, v152
	v_add_f32_e32 v152, v206, v152
	v_add_f32_e32 v152, v207, v152
	v_add_f32_e32 v152, v208, v152
	v_add_f32_e32 v152, v150, v152
	v_exp_f32_e32 v229, v155
	v_add_f32_e32 v152, v151, v152
	v_add_f32_e32 v152, v209, v152
	v_add_f32_e32 v152, v210, v152
	v_mfma_f32_32x32x16_bf16 v[66:81], v[236:239], v[240:243], v[66:81]
	v_exp_f32_e32 v237, v231
	v_add_f32_e32 v152, v211, v152
	v_exp_f32_e32 v238, v232
	v_add_f32_e32 v152, v229, v152
	v_add_f32_e32 v152, v233, v152
	v_add_f32_e32 v152, v149, v152
	v_add_f32_e32 v152, v237, v152
	v_add_f32_e32 v152, v238, v152
	v_add_f32_e32 v235, v148, v152
	v_mov_b32_e32 v236, v235
	v_cvt_pk_bf16_f32 v152, v141, v143
	v_cvt_pk_bf16_f32 v155, v140, v142
	v_permlane32_swap_b32_e32 v235, v236
	v_permlane32_swap_b32_e32 v152, v154
	v_permlane32_swap_b32_e32 v153, v155
	v_cvt_pk_bf16_f32 v157, v138, v139
	v_cvt_pk_bf16_f32 v158, v132, v133
	v_cvt_pk_bf16_f32 v159, v134, v136
	v_cvt_pk_bf16_f32 v204, v204, v205
	v_cvt_pk_bf16_f32 v205, v206, v207
	v_cvt_pk_bf16_f32 v206, v208, v150
	v_cvt_pk_bf16_f32 v207, v151, v209
	v_cvt_pk_bf16_f32 v231, v229, v233
	v_cvt_pk_bf16_f32 v232, v149, v237
	v_cvt_pk_bf16_f32 v233, v238, v148
	v_permlane32_swap_b32_e32 v156, v158
	v_permlane32_swap_b32_e32 v157, v159
	v_permlane32_swap_b32_e32 v204, v206
	v_permlane32_swap_b32_e32 v205, v207
	v_permlane32_swap_b32_e32 v230, v232
	v_permlane32_swap_b32_e32 v231, v233
	ds_read_b64_tr_b16 v[238:239], v199 offset:0
	ds_read_b64_tr_b16 v[240:241], v199 offset:0x800
	ds_read_b64_tr_b16 v[242:243], v199 offset:0x1000
	ds_read_b64_tr_b16 v[244:245], v199 offset:0x1800
	ds_read_b64_tr_b16 v[246:247], v199 offset:0x2000
	ds_read_b64_tr_b16 v[248:249], v199 offset:0x2800
	ds_read_b64_tr_b16 v[208:209], v199 offset:0x3000
	ds_read_b64_tr_b16 v[210:211], v199 offset:0x3800
	s_waitcnt lgkmcnt(0)
	s_nop 0
	v_mfma_f32_32x32x16_bf16 v[2:17], v[152:155], v[238:241], v[2:17]
	v_mfma_f32_32x32x16_bf16 v[2:17], v[156:159], v[242:245], v[2:17]
	v_mfma_f32_32x32x16_bf16 v[2:17], v[204:207], v[246:249], v[2:17]
	v_mfma_f32_32x32x16_bf16 v[2:17], v[230:233], v[208:211], v[2:17]
	ds_read_b64_tr_b16 v[208:209], v199 offset:0x200
	ds_read_b64_tr_b16 v[210:211], v199 offset:0xa00
	ds_read_b64_tr_b16 v[238:239], v199 offset:0x1200
	ds_read_b64_tr_b16 v[240:241], v199 offset:0x1a00
	ds_read_b64_tr_b16 v[242:243], v199 offset:0x2200
	ds_read_b64_tr_b16 v[244:245], v199 offset:0x2a00
	ds_read_b64_tr_b16 v[246:247], v199 offset:0x3200
	ds_read_b64_tr_b16 v[248:249], v199 offset:0x3a00
	s_waitcnt lgkmcnt(0)
	s_nop 0
	v_mfma_f32_32x32x16_bf16 v[50:65], v[152:155], v[208:211], v[50:65]
	ds_read_b64_tr_b16 v[208:209], v199 offset:0x400
	ds_read_b64_tr_b16 v[210:211], v199 offset:0xc00
	v_mfma_f32_32x32x16_bf16 v[50:65], v[156:159], v[238:241], v[50:65]
	ds_read_b64_tr_b16 v[238:239], v199 offset:0x1400
	ds_read_b64_tr_b16 v[240:241], v199 offset:0x1c00
	v_mfma_f32_32x32x16_bf16 v[50:65], v[204:207], v[242:245], v[50:65]
	ds_read_b64_tr_b16 v[242:243], v199 offset:0x2400
	ds_read_b64_tr_b16 v[244:245], v199 offset:0x2c00
	v_mfma_f32_32x32x16_bf16 v[50:65], v[230:233], v[246:249], v[50:65]
	ds_read_b64_tr_b16 v[246:247], v199 offset:0x3400
	ds_read_b64_tr_b16 v[248:249], v199 offset:0x3c00
	s_waitcnt lgkmcnt(0)
	v_mfma_f32_32x32x16_bf16 v[34:49], v[152:155], v[208:211], v[34:49]
	ds_read_b64_tr_b16 v[208:209], v199 offset:0x600
	ds_read_b64_tr_b16 v[210:211], v199 offset:0xe00
	v_mfma_f32_32x32x16_bf16 v[34:49], v[156:159], v[238:241], v[34:49]
	ds_read_b64_tr_b16 v[238:239], v199 offset:0x1600
	ds_read_b64_tr_b16 v[240:241], v199 offset:0x1e00
	v_mfma_f32_32x32x16_bf16 v[34:49], v[204:207], v[242:245], v[34:49]
	ds_read_b64_tr_b16 v[242:243], v199 offset:0x2600
	ds_read_b64_tr_b16 v[244:245], v199 offset:0x2e00
	v_mfma_f32_32x32x16_bf16 v[34:49], v[230:233], v[246:249], v[34:49]
	ds_read_b64_tr_b16 v[246:247], v199 offset:0x3600
	ds_read_b64_tr_b16 v[248:249], v199 offset:0x3e00
	s_waitcnt lgkmcnt(0)
	v_mfma_f32_32x32x16_bf16 v[18:33], v[152:155], v[208:211], v[18:33]
	v_max_f32_e32 v152, v83, v83
	v_max_f32_e32 v153, v82, v82
	v_max_f32_e32 v152, v153, v152
	v_max3_f32 v152, v152, v84, v85
	v_max3_f32 v152, v152, v86, v87
	v_max3_f32 v152, v152, v88, v89
	v_max3_f32 v152, v152, v90, v91
	v_max3_f32 v152, v152, v92, v93
	v_max3_f32 v152, v152, v94, v95
	v_mfma_f32_32x32x16_bf16 v[18:33], v[156:159], v[238:241], v[18:33]
	v_max3_f32 v152, v152, v96, v97
	v_max3_f32 v152, v152, v66, v67
	v_max3_f32 v152, v152, v68, v69
	v_max3_f32 v152, v152, v70, v71
	v_max3_f32 v152, v152, v72, v73
	v_max3_f32 v152, v152, v74, v75
	v_max3_f32 v152, v152, v76, v77
	v_max3_f32 v152, v152, v78, v79
	v_mfma_f32_32x32x16_bf16 v[18:33], v[204:207], v[242:245], v[18:33]
	v_max3_f32 v152, v152, v80, v81
	v_mov_b32_e32 v153, v152
	s_nop 1
	v_permlane32_swap_b32_e32 v152, v153
	v_max_f32_e32 v153, v153, v153
	v_max_f32_e32 v152, v152, v152
	v_max_f32_e32 v152, v152, v153
	v_sub_f32_e32 v153, v152, v214
	v_cmp_ge_f32_e32 vcc, s5, v153
	v_max_f32_e32 v153, v214, v214
	v_max_f32_e32 v153, v153, v152
	v_mfma_f32_32x32x16_bf16 v[18:33], v[230:233], v[246:249], v[18:33]
	v_sub_f32_e32 v152, v214, v153
	v_mul_f32_e32 v152, 0x3dd53b94, v152
	v_exp_f32_e32 v152, v152
	s_cmp_eq_u64 vcc, exec
	s_cselect_b64 s[40:41], -1, 0
	s_barrier
	s_add_i32 m0, s100, 0x4000
	v_cndmask_b32_e64 v152, v152, 1.0, s[40:41]
	global_load_lds_dwordx4 v178, s[14:15]
	s_add_i32 m0, s100, 0x4400
	v_cmp_gt_f32_e32 vcc, 1.0, v152
	global_load_lds_dwordx4 v179, s[14:15]
	s_cbranch_vccz .LBB0_863
	s_and_saveexec_b64 s[0:1], s[38:39]
	ds_write_b32 v197, v152 offset:128
	s_or_b64 exec, exec, s[0:1]
	s_waitcnt lgkmcnt(0)
	ds_read_b128 v[132:135], v193 offset:224
	ds_read_b128 v[136:139], v193 offset:192
	ds_read_b128 v[140:143], v193 offset:160
	ds_read_b128 v[144:147], v193 offset:128
	s_waitcnt lgkmcnt(3)
	v_pk_mul_f32 v[16:17], v[16:17], v[134:135]
	s_waitcnt lgkmcnt(2)
	v_pk_mul_f32 v[12:13], v[12:13], v[138:139]
	s_waitcnt lgkmcnt(1)
	v_pk_mul_f32 v[8:9], v[8:9], v[142:143]
	s_waitcnt lgkmcnt(0)
	v_pk_mul_f32 v[4:5], v[4:5], v[146:147]
	v_pk_mul_f32 v[14:15], v[14:15], v[132:133]
	v_pk_mul_f32 v[10:11], v[10:11], v[136:137]
	v_pk_mul_f32 v[6:7], v[6:7], v[140:141]
	v_pk_mul_f32 v[2:3], v[2:3], v[144:145]
	v_pk_mul_f32 v[64:65], v[64:65], v[134:135]
	v_pk_mul_f32 v[60:61], v[60:61], v[138:139]
	v_pk_mul_f32 v[56:57], v[56:57], v[142:143]
	v_pk_mul_f32 v[52:53], v[52:53], v[146:147]
	v_pk_mul_f32 v[62:63], v[62:63], v[132:133]
	v_pk_mul_f32 v[58:59], v[58:59], v[136:137]
	v_pk_mul_f32 v[54:55], v[54:55], v[140:141]
	v_pk_mul_f32 v[50:51], v[50:51], v[144:145]
	v_pk_mul_f32 v[48:49], v[48:49], v[134:135]
	v_pk_mul_f32 v[44:45], v[44:45], v[138:139]
	v_pk_mul_f32 v[40:41], v[40:41], v[142:143]
	v_pk_mul_f32 v[36:37], v[36:37], v[146:147]
	v_pk_mul_f32 v[46:47], v[46:47], v[132:133]
	v_pk_mul_f32 v[42:43], v[42:43], v[136:137]
	v_pk_mul_f32 v[38:39], v[38:39], v[140:141]
	v_pk_mul_f32 v[34:35], v[34:35], v[144:145]
	v_pk_mul_f32 v[32:33], v[32:33], v[134:135]
	v_pk_mul_f32 v[28:29], v[28:29], v[138:139]
	v_pk_mul_f32 v[24:25], v[24:25], v[142:143]
	v_pk_mul_f32 v[20:21], v[20:21], v[146:147]
	v_pk_mul_f32 v[30:31], v[30:31], v[132:133]
	v_pk_mul_f32 v[26:27], v[26:27], v[136:137]
	v_pk_mul_f32 v[22:23], v[22:23], v[140:141]
	v_pk_mul_f32 v[18:19], v[18:19], v[144:145]
.LBB0_863:
	v_cndmask_b32_e64 v214, v153, v214, s[40:41]
	v_mul_f32_e32 v138, 0xbdd53b94, v214
	v_mov_b32_e32 v139, v138
	v_fmamk_f32 v82, v82, 0x3dd53b94, v138
	v_fmamk_f32 v83, v83, 0x3dd53b94, v138
	v_fmamk_f32 v84, v84, 0x3dd53b94, v138
	v_fmamk_f32 v85, v85, 0x3dd53b94, v138
	v_fmamk_f32 v86, v86, 0x3dd53b94, v138
	v_fmamk_f32 v87, v87, 0x3dd53b94, v138
	v_fmamk_f32 v88, v88, 0x3dd53b94, v138
	v_fmamk_f32 v89, v89, 0x3dd53b94, v138
	v_fmamk_f32 v90, v90, 0x3dd53b94, v138
	v_fmamk_f32 v91, v91, 0x3dd53b94, v138
	v_fmamk_f32 v92, v92, 0x3dd53b94, v138
	v_fmamk_f32 v93, v93, 0x3dd53b94, v138
	v_fmamk_f32 v94, v94, 0x3dd53b94, v138
	v_fmamk_f32 v95, v95, 0x3dd53b94, v138
	v_fmamk_f32 v96, v96, 0x3dd53b94, v138
	v_fmac_f32_e32 v139, 0x3dd53b94, v97
	v_exp_f32_e32 v153, v82
	v_exp_f32_e32 v154, v83
	v_exp_f32_e32 v230, v84
	v_exp_f32_e32 v231, v85
	v_exp_f32_e32 v232, v86
	v_exp_f32_e32 v233, v87
	v_exp_f32_e32 v155, v88
	v_exp_f32_e32 v229, v89
	v_exp_f32_e32 v151, v90
	v_exp_f32_e32 v156, v91
	v_exp_f32_e32 v157, v92
	v_exp_f32_e32 v158, v93
	v_exp_f32_e32 v148, v94
	v_exp_f32_e32 v149, v95
	v_exp_f32_e32 v150, v96
	v_exp_f32_e32 v159, v139
	v_pk_fma_f32 v[144:145], v[66:67], s[30:31], v[138:139] op_sel_hi:[1,0,0]
	v_add_f32_e32 v66, v227, v228
	v_fmac_f32_e32 v66, v213, v198
	v_add_f32_e32 v198, v235, v236
	s_addk_i32 s12, 0x80
	s_addk_i32 s13, 0x80
	v_pk_fma_f32 v[142:143], v[68:69], s[30:31], v[138:139] op_sel_hi:[1,0,0]
	v_pk_fma_f32 v[136:137], v[70:71], s[30:31], v[138:139] op_sel_hi:[1,0,0]
	v_pk_fma_f32 v[134:135], v[72:73], s[30:31], v[138:139] op_sel_hi:[1,0,0]
	v_pk_fma_f32 v[132:133], v[74:75], s[30:31], v[138:139] op_sel_hi:[1,0,0]
	v_pk_fma_f32 v[146:147], v[76:77], s[30:31], v[138:139] op_sel_hi:[1,0,0]
	v_pk_fma_f32 v[140:141], v[78:79], s[30:31], v[138:139] op_sel_hi:[1,0,0]
	v_pk_fma_f32 v[138:139], v[80:81], s[30:31], v[138:139] op_sel_hi:[1,0,0]
	v_fmac_f32_e32 v198, v66, v234
	s_cmp_gt_u32 s11, 32
	s_waitcnt vmcnt(2) lgkmcnt(0)
	s_barrier
	s_cbranch_scc1 .LBB0_865
	v_mov_b32_e32 v213, v152
	s_branch .LBB0_855
.LBB0_865:
	ds_read_b128 v[66:69], v183 offset:57344
	ds_read_b128 v[70:73], v226 offset:57344
	v_add_f32_e32 v98, 0, v153
	v_add_f32_e32 v98, v154, v98
	v_add_f32_e32 v98, v230, v98
	s_waitcnt lgkmcnt(1)
	v_mfma_f32_32x32x16_bf16 v[82:97], v[66:69], v[128:131], 0
	v_add_f32_e32 v98, v231, v98
	v_add_f32_e32 v98, v232, v98
	v_add_f32_e32 v98, v233, v98
	v_add_f32_e32 v98, v155, v98
	v_add_f32_e32 v98, v229, v98
	v_add_f32_e32 v98, v151, v98
	v_add_f32_e32 v98, v156, v98
	s_waitcnt lgkmcnt(0)
	v_mfma_f32_32x32x16_bf16 v[66:81], v[70:73], v[128:131], 0
	ds_read_b128 v[128:131], v184 offset:57344
	ds_read_b128 v[162:165], v225 offset:57344
	v_add_f32_e32 v98, v157, v98
	v_add_f32_e32 v98, v158, v98
	v_add_f32_e32 v98, v148, v98
	v_add_f32_e32 v98, v149, v98
	v_add_f32_e32 v98, v150, v98
	v_add_f32_e32 v98, v159, v98
	s_waitcnt lgkmcnt(1)
	v_mfma_f32_32x32x16_bf16 v[82:97], v[128:131], v[124:127], v[82:97]
	s_waitcnt lgkmcnt(0)
	v_mfma_f32_32x32x16_bf16 v[66:81], v[162:165], v[124:127], v[66:81]
	ds_read_b128 v[124:127], v185 offset:57344
	ds_read_b128 v[128:131], v224 offset:57344
	s_waitcnt lgkmcnt(1)
	v_mfma_f32_32x32x16_bf16 v[82:97], v[124:127], v[120:123], v[82:97]
	s_waitcnt lgkmcnt(0)
	v_mfma_f32_32x32x16_bf16 v[66:81], v[128:131], v[120:123], v[66:81]
	ds_read_b128 v[120:123], v186 offset:57344
	ds_read_b128 v[124:127], v223 offset:57344
	s_waitcnt lgkmcnt(1)
	v_mfma_f32_32x32x16_bf16 v[82:97], v[120:123], v[116:119], v[82:97]
	s_waitcnt lgkmcnt(0)
	v_mfma_f32_32x32x16_bf16 v[66:81], v[124:127], v[116:119], v[66:81]
	ds_read_b128 v[116:119], v187 offset:57344
	ds_read_b128 v[120:123], v222 offset:57344
	v_exp_f32_e32 v124, v139
	s_waitcnt lgkmcnt(1)
	v_mfma_f32_32x32x16_bf16 v[82:97], v[116:119], v[112:115], v[82:97]
	s_waitcnt lgkmcnt(0)
	v_mfma_f32_32x32x16_bf16 v[66:81], v[120:123], v[112:115], v[66:81]
	ds_read_b128 v[112:115], v188 offset:57344
	ds_read_b128 v[116:119], v221 offset:57344
	v_exp_f32_e32 v120, v147
	v_exp_f32_e32 v121, v140
	v_exp_f32_e32 v122, v141
	v_exp_f32_e32 v123, v138
	s_waitcnt lgkmcnt(1)
	v_mfma_f32_32x32x16_bf16 v[82:97], v[112:115], v[108:111], v[82:97]
	s_waitcnt lgkmcnt(0)
	v_mfma_f32_32x32x16_bf16 v[66:81], v[116:119], v[108:111], v[66:81]
	ds_read_b128 v[108:111], v189 offset:57344
	ds_read_b128 v[112:115], v220 offset:57344
	v_exp_f32_e32 v116, v135
	v_exp_f32_e32 v117, v132
	v_exp_f32_e32 v118, v133
	v_exp_f32_e32 v119, v146
	s_waitcnt lgkmcnt(1)
	v_mfma_f32_32x32x16_bf16 v[82:97], v[108:111], v[104:107], v[82:97]
	s_waitcnt lgkmcnt(0)
	v_mfma_f32_32x32x16_bf16 v[66:81], v[112:115], v[104:107], v[66:81]
	ds_read_b128 v[104:107], v190 offset:57344
	ds_read_b128 v[108:111], v219 offset:57344
	v_exp_f32_e32 v112, v143
	v_exp_f32_e32 v113, v136
	v_exp_f32_e32 v114, v137
	v_exp_f32_e32 v115, v134
	s_waitcnt lgkmcnt(1)
	v_mfma_f32_32x32x16_bf16 v[82:97], v[104:107], v[100:103], v[82:97]
	s_waitcnt lgkmcnt(0)
	v_mfma_f32_32x32x16_bf16 v[66:81], v[108:111], v[100:103], v[66:81]
	ds_read_b128 v[100:103], v191 offset:57344
	ds_read_b128 v[104:107], v218 offset:57344
	ds_read_b128 v[108:111], v192
	s_waitcnt lgkmcnt(0)
	v_mfma_f32_32x32x16_bf16 v[82:97], v[100:103], v[108:111], v[82:97]
	v_mfma_f32_32x32x16_bf16 v[66:81], v[104:107], v[108:111], v[66:81]
	ds_read_b128 v[100:103], v194 offset:57344
	ds_read_b128 v[104:107], v217 offset:57344
	ds_read_b128 v[108:111], v176
	s_waitcnt lgkmcnt(0)
	v_mfma_f32_32x32x16_bf16 v[82:97], v[100:103], v[108:111], v[82:97]
	v_mfma_f32_32x32x16_bf16 v[66:81], v[104:107], v[108:111], v[66:81]
	ds_read_b128 v[100:103], v195 offset:57344
	ds_read_b128 v[104:107], v216 offset:57344
	ds_read_b128 v[108:111], v177
	s_waitcnt lgkmcnt(0)
	v_mfma_f32_32x32x16_bf16 v[82:97], v[100:103], v[108:111], v[82:97]
	v_mfma_f32_32x32x16_bf16 v[66:81], v[104:107], v[108:111], v[66:81]
	ds_read_b128 v[100:103], v196 offset:57344
	ds_read_b128 v[104:107], v215 offset:57344
	ds_read_b128 v[108:111], v175
	s_waitcnt lgkmcnt(0)
	v_mfma_f32_32x32x16_bf16 v[82:97], v[100:103], v[108:111], v[82:97]
	v_exp_f32_e32 v101, v144
	v_cvt_pk_bf16_f32 v102, v153, v154
	v_cvt_pk_bf16_f32 v103, v230, v231
	v_add_f32_e32 v98, v101, v98
	v_mfma_f32_32x32x16_bf16 v[66:81], v[104:107], v[108:111], v[66:81]
	v_exp_f32_e32 v110, v145
	v_exp_f32_e32 v111, v142
	v_cvt_pk_bf16_f32 v104, v232, v233
	v_cvt_pk_bf16_f32 v105, v155, v229
	v_add_f32_e32 v98, v110, v98
	v_add_f32_e32 v98, v111, v98
	v_add_f32_e32 v98, v112, v98
	v_add_f32_e32 v98, v113, v98
	v_add_f32_e32 v98, v114, v98
	v_add_f32_e32 v98, v115, v98
	v_add_f32_e32 v98, v116, v98
	v_add_f32_e32 v98, v117, v98
	v_add_f32_e32 v98, v118, v98
	v_add_f32_e32 v98, v119, v98
	v_add_f32_e32 v98, v120, v98
	v_add_f32_e32 v98, v121, v98
	v_add_f32_e32 v98, v122, v98
	v_add_f32_e32 v98, v123, v98
	v_add_f32_e32 v98, v124, v98
	v_mov_b32_e32 v100, v98
	s_nop 1
	v_permlane32_swap_b32_e32 v98, v100
	v_permlane32_swap_b32_e32 v102, v104
	v_cvt_pk_bf16_f32 v106, v151, v156
	v_cvt_pk_bf16_f32 v107, v157, v158
	v_cvt_pk_bf16_f32 v108, v148, v149
	v_cvt_pk_bf16_f32 v109, v150, v159
	v_cvt_pk_bf16_f32 v110, v101, v110
	v_cvt_pk_bf16_f32 v111, v111, v112
	v_cvt_pk_bf16_f32 v112, v113, v114
	v_cvt_pk_bf16_f32 v113, v115, v116
	v_cvt_pk_bf16_f32 v114, v117, v118
	v_cvt_pk_bf16_f32 v115, v119, v120
	v_cvt_pk_bf16_f32 v116, v121, v122
	v_cvt_pk_bf16_f32 v117, v123, v124
	v_permlane32_swap_b32_e32 v103, v105
	v_permlane32_swap_b32_e32 v106, v108
	v_permlane32_swap_b32_e32 v107, v109
	v_permlane32_swap_b32_e32 v110, v112
	v_permlane32_swap_b32_e32 v111, v113
	v_permlane32_swap_b32_e32 v114, v116
	v_permlane32_swap_b32_e32 v115, v117
	ds_read_b64_tr_b16 v[118:119], v174 offset:0
	ds_read_b64_tr_b16 v[120:121], v174 offset:0x800
	ds_read_b64_tr_b16 v[122:123], v174 offset:0x1000
	ds_read_b64_tr_b16 v[124:125], v174 offset:0x1800
	ds_read_b64_tr_b16 v[126:127], v174 offset:0x2000
	ds_read_b64_tr_b16 v[128:129], v174 offset:0x2800
	ds_read_b64_tr_b16 v[130:131], v174 offset:0x3000
	ds_read_b64_tr_b16 v[132:133], v174 offset:0x3800
	s_waitcnt lgkmcnt(0)
	s_nop 0
	v_mfma_f32_32x32x16_bf16 v[2:17], v[102:105], v[118:121], v[2:17]
	ds_read_b64_tr_b16 v[118:119], v174 offset:0x200
	ds_read_b64_tr_b16 v[120:121], v174 offset:0xa00
	v_mfma_f32_32x32x16_bf16 v[2:17], v[106:109], v[122:125], v[2:17]
	ds_read_b64_tr_b16 v[122:123], v174 offset:0x1200
	ds_read_b64_tr_b16 v[124:125], v174 offset:0x1a00
	v_mfma_f32_32x32x16_bf16 v[2:17], v[110:113], v[126:129], v[2:17]
	ds_read_b64_tr_b16 v[126:127], v174 offset:0x2200
	ds_read_b64_tr_b16 v[128:129], v174 offset:0x2a00
	v_mfma_f32_32x32x16_bf16 v[2:17], v[114:117], v[130:133], v[2:17]
	ds_read_b64_tr_b16 v[130:131], v174 offset:0x3200
	ds_read_b64_tr_b16 v[132:133], v174 offset:0x3a00
	s_waitcnt lgkmcnt(0)
	v_mfma_f32_32x32x16_bf16 v[50:65], v[102:105], v[118:121], v[50:65]
	ds_read_b64_tr_b16 v[118:119], v174 offset:0x400
	ds_read_b64_tr_b16 v[120:121], v174 offset:0xc00
	v_mfma_f32_32x32x16_bf16 v[50:65], v[106:109], v[122:125], v[50:65]
	ds_read_b64_tr_b16 v[122:123], v174 offset:0x1400
	ds_read_b64_tr_b16 v[124:125], v174 offset:0x1c00
	v_mfma_f32_32x32x16_bf16 v[50:65], v[110:113], v[126:129], v[50:65]
	ds_read_b64_tr_b16 v[126:127], v174 offset:0x2400
	ds_read_b64_tr_b16 v[128:129], v174 offset:0x2c00
	v_mfma_f32_32x32x16_bf16 v[50:65], v[114:117], v[130:133], v[50:65]
	ds_read_b64_tr_b16 v[130:131], v174 offset:0x3400
	ds_read_b64_tr_b16 v[132:133], v174 offset:0x3c00
	s_waitcnt lgkmcnt(0)
	v_mfma_f32_32x32x16_bf16 v[34:49], v[102:105], v[118:121], v[34:49]
	ds_read_b64_tr_b16 v[118:119], v174 offset:0x600
	ds_read_b64_tr_b16 v[120:121], v174 offset:0xe00
	v_mfma_f32_32x32x16_bf16 v[34:49], v[106:109], v[122:125], v[34:49]
	ds_read_b64_tr_b16 v[122:123], v174 offset:0x1600
	ds_read_b64_tr_b16 v[124:125], v174 offset:0x1e00
	v_mfma_f32_32x32x16_bf16 v[34:49], v[110:113], v[126:129], v[34:49]
	ds_read_b64_tr_b16 v[126:127], v174 offset:0x2600
	ds_read_b64_tr_b16 v[128:129], v174 offset:0x2e00
	v_mfma_f32_32x32x16_bf16 v[34:49], v[114:117], v[130:133], v[34:49]
	ds_read_b64_tr_b16 v[130:131], v174 offset:0x3600
	ds_read_b64_tr_b16 v[132:133], v174 offset:0x3e00
	s_waitcnt lgkmcnt(0)
	v_mfma_f32_32x32x16_bf16 v[18:33], v[102:105], v[118:121], v[18:33]
	v_max_f32_e32 v101, v83, v83
	v_max_f32_e32 v102, v82, v82
	v_max_f32_e32 v101, v102, v101
	v_max3_f32 v101, v101, v84, v85
	v_max3_f32 v101, v101, v86, v87
	v_max3_f32 v101, v101, v88, v89
	v_max3_f32 v101, v101, v90, v91
	v_max3_f32 v101, v101, v92, v93
	v_max3_f32 v101, v101, v94, v95
	v_mfma_f32_32x32x16_bf16 v[18:33], v[106:109], v[122:125], v[18:33]
	v_max3_f32 v101, v101, v96, v97
	v_max3_f32 v101, v101, v66, v67
	v_max3_f32 v101, v101, v68, v69
	v_max3_f32 v101, v101, v70, v71
	v_max3_f32 v101, v101, v72, v73
	v_max3_f32 v101, v101, v74, v75
	v_max3_f32 v101, v101, v76, v77
	v_max3_f32 v101, v101, v78, v79
	v_mfma_f32_32x32x16_bf16 v[18:33], v[110:113], v[126:129], v[18:33]
	v_max3_f32 v101, v101, v80, v81
	v_mov_b32_e32 v102, v101
	s_nop 1
	v_permlane32_swap_b32_e32 v101, v102
	v_max_f32_e32 v102, v102, v102
	v_max_f32_e32 v101, v101, v101
	v_max_f32_e32 v101, v101, v102
	v_sub_f32_e32 v102, v101, v214
	v_cmp_ge_f32_e32 vcc, s5, v102
	v_max_f32_e32 v102, v214, v214
	v_max_f32_e32 v102, v102, v101
	v_mfma_f32_32x32x16_bf16 v[18:33], v[114:117], v[130:133], v[18:33]
	v_sub_f32_e32 v101, v214, v102
	v_mul_f32_e32 v101, 0x3dd53b94, v101
	v_exp_f32_e32 v101, v101
	s_cmp_eq_u64 vcc, exec
	s_cselect_b64 s[0:1], -1, 0
	v_cndmask_b32_e64 v101, v101, 1.0, s[0:1]
	v_cmp_gt_f32_e32 vcc, 1.0, v101
	s_waitcnt vmcnt(0)
	s_barrier
	s_cbranch_vccz .LBB0_869
	s_mov_b64 s[22:23], exec
	s_and_b64 s[8:9], s[22:23], s[38:39]
	v_mov_b32_e32 v241, v203
	v_mov_b32_e32 v242, v202
	s_mov_b64 exec, s[8:9]
	ds_write_b32 v197, v101 offset:128
	s_or_b64 exec, exec, s[22:23]
	s_waitcnt lgkmcnt(0)
	ds_read_b128 v[104:107], v193 offset:224
	ds_read_b128 v[108:111], v193 offset:192
	ds_read_b128 v[112:115], v193 offset:160
	ds_read_b128 v[116:119], v193 offset:128
	v_mov_b32_e32 v203, v201
	s_waitcnt lgkmcnt(3)
	v_pk_mul_f32 v[16:17], v[16:17], v[106:107]
	s_waitcnt lgkmcnt(2)
	v_pk_mul_f32 v[12:13], v[12:13], v[110:111]
	s_waitcnt lgkmcnt(1)
	v_pk_mul_f32 v[8:9], v[8:9], v[114:115]
	s_waitcnt lgkmcnt(0)
	v_pk_mul_f32 v[4:5], v[4:5], v[118:119]
	v_pk_mul_f32 v[14:15], v[14:15], v[104:105]
	v_pk_mul_f32 v[10:11], v[10:11], v[108:109]
	v_pk_mul_f32 v[6:7], v[6:7], v[112:113]
	v_pk_mul_f32 v[2:3], v[2:3], v[116:117]
	v_pk_mul_f32 v[64:65], v[64:65], v[106:107]
	v_pk_mul_f32 v[60:61], v[60:61], v[110:111]
	v_pk_mul_f32 v[56:57], v[56:57], v[114:115]
	v_pk_mul_f32 v[52:53], v[52:53], v[118:119]
	v_pk_mul_f32 v[62:63], v[62:63], v[104:105]
	v_pk_mul_f32 v[58:59], v[58:59], v[108:109]
	v_pk_mul_f32 v[54:55], v[54:55], v[112:113]
	v_pk_mul_f32 v[50:51], v[50:51], v[116:117]
	v_pk_mul_f32 v[48:49], v[48:49], v[106:107]
	v_pk_mul_f32 v[44:45], v[44:45], v[110:111]
	v_pk_mul_f32 v[40:41], v[40:41], v[114:115]
	v_pk_mul_f32 v[36:37], v[36:37], v[118:119]
	v_pk_mul_f32 v[46:47], v[46:47], v[104:105]
	v_pk_mul_f32 v[42:43], v[42:43], v[108:109]
	v_pk_mul_f32 v[38:39], v[38:39], v[112:113]
	v_pk_mul_f32 v[34:35], v[34:35], v[116:117]
	v_pk_mul_f32 v[32:33], v[32:33], v[106:107]
	v_pk_mul_f32 v[28:29], v[28:29], v[110:111]
	v_pk_mul_f32 v[24:25], v[24:25], v[114:115]
	v_pk_mul_f32 v[20:21], v[20:21], v[118:119]
	v_pk_mul_f32 v[30:31], v[30:31], v[104:105]
	v_pk_mul_f32 v[26:27], v[26:27], v[108:109]
	v_pk_mul_f32 v[22:23], v[22:23], v[112:113]
	v_pk_mul_f32 v[18:19], v[18:19], v[116:117]
	s_branch .LBB0_870
